# v063 + two staggered polls in flight in the grid-barrier wait loops (s_sleep 6 stagger)
# baseline (speedup 1.0000x reference)
.LBB0_69:
	s_lshl_b32 s8, s3, 8
	s_add_u32 s8, s34, s8
	s_addc_u32 s9, s35, 0
	v_mov_b32_e32 v3, 0x1000
	v_mov_b32_e32 v5, 1
	global_atomic_add v5, v3, v5, s[8:9] offset:1024 sc0
	v_cvt_f32_u32_e32 v3, v4
	v_sub_u32_e32 v6, 0, v4
	v_rcp_iflag_f32_e32 v3, v3
	s_nop 0
	v_mul_f32_e32 v3, 0x4f7ffffe, v3
	v_cvt_u32_f32_e32 v3, v3
	v_mul_lo_u32 v6, v6, v3
	v_mul_hi_u32 v6, v3, v6
	v_add_u32_e32 v3, v3, v6
	s_waitcnt vmcnt(0)
	v_mul_hi_u32 v3, v5, v3
	v_mul_lo_u32 v6, v3, v4
	v_sub_u32_e32 v6, v5, v6
	v_add_u32_e32 v7, 1, v3
	v_cmp_ge_u32_e32 vcc, v6, v4
	v_add_u32_e32 v5, 1, v5
	s_nop 0
	v_cndmask_b32_e32 v3, v3, v7, vcc
	v_sub_u32_e32 v7, v6, v4
	v_cndmask_b32_e32 v6, v6, v7, vcc
	v_add_u32_e32 v7, 1, v3
	v_cmp_ge_u32_e32 vcc, v6, v4
	s_nop 1
	v_cndmask_b32_e32 v3, v3, v7, vcc
	v_mul_lo_u32 v6, v4, v3
	v_add_u32_e32 v4, v6, v4
	v_cmp_ne_u32_e32 vcc, v5, v4
	s_and_saveexec_b64 s[14:15], vcc
	s_xor_b64 s[14:15], exec, s[14:15]
	s_cbranch_execz .LBB0_83
	s_waitcnt lgkmcnt(0)
	v_mad_u32_u24 v6, v3, v2, v2
	s_add_u32 s20, s38, 0x1d6c5400
	s_addc_u32 s21, s39, 0
	v_mov_b32_e32 v2, 0
	s_mov_b32 s48, 0
	global_load_dword v4, v2, s[20:21] sc1
.Lmy_bf_0:
	s_sleep 6
	global_load_dword v5, v2, s[20:21] sc1
	s_waitcnt vmcnt(1)
	v_sub_u32_e32 v4, v4, v6
	v_cmp_gt_i32_e32 vcc, 0, v4
	s_cbranch_vccz .Lmy_bf_0d
	s_sleep 6
	global_load_dword v4, v2, s[20:21] sc1
	s_waitcnt vmcnt(1)
	v_sub_u32_e32 v5, v5, v6
	v_cmp_gt_i32_e32 vcc, 0, v5
	s_cbranch_vccz .Lmy_bf_0d
	s_add_i32 s48, s48, 1
	s_cmp_lt_u32 s48, 0x100000
	s_cbranch_scc1 .Lmy_bf_0
.Lmy_bf_0d:
	s_waitcnt vmcnt(0)
	buffer_inv sc1
	s_waitcnt vmcnt(0)
.LBB0_83:
	s_andn2_saveexec_b64 s[14:15], s[14:15]
	s_cbranch_execz .LBB0_101
	buffer_wbl2 sc1
	s_waitcnt lgkmcnt(0)
	v_mad_u32_u24 v6, v3, v2, v2
	s_waitcnt vmcnt(0)
	v_mov_b32_e32 v4, 0x1d6c5000
	v_mov_b32_e32 v5, 1
	global_atomic_add v4, v5, s[38:39] offset:1024
	s_add_u32 s16, s38, 0x1d6c5400
	s_addc_u32 s17, s39, 0
	v_mov_b32_e32 v2, 0
	s_mov_b32 s48, 0
	global_load_dword v4, v2, s[16:17] sc1
.Lmy_bl_0:
	s_sleep 6
	global_load_dword v5, v2, s[16:17] sc1
	s_waitcnt vmcnt(1)
	v_sub_u32_e32 v4, v4, v6
	v_cmp_gt_i32_e32 vcc, 0, v4
	s_cbranch_vccz .Lmy_bl_0d
	s_sleep 6
	global_load_dword v4, v2, s[16:17] sc1
	s_waitcnt vmcnt(1)
	v_sub_u32_e32 v5, v5, v6
	v_cmp_gt_i32_e32 vcc, 0, v5
	s_cbranch_vccz .Lmy_bl_0d
	s_add_i32 s48, s48, 1
	s_cmp_lt_u32 s48, 0x100000
	s_cbranch_scc1 .Lmy_bl_0

.LBB0_451:
	s_lshl_b32 s8, s3, 8
	s_add_u32 s8, s34, s8
	s_addc_u32 s9, s35, 0
	v_mov_b32_e32 v3, 0x1000
	v_mov_b32_e32 v5, 1
	global_atomic_add v5, v3, v5, s[8:9] offset:1024 sc0
	v_cvt_f32_u32_e32 v3, v4
	v_sub_u32_e32 v6, 0, v4
	v_rcp_iflag_f32_e32 v3, v3
	s_nop 0
	v_mul_f32_e32 v3, 0x4f7ffffe, v3
	v_cvt_u32_f32_e32 v3, v3
	v_mul_lo_u32 v6, v6, v3
	v_mul_hi_u32 v6, v3, v6
	v_add_u32_e32 v3, v3, v6
	s_waitcnt vmcnt(0)
	v_mul_hi_u32 v3, v5, v3
	v_mul_lo_u32 v6, v3, v4
	v_sub_u32_e32 v6, v5, v6
	v_add_u32_e32 v7, 1, v3
	v_cmp_ge_u32_e32 vcc, v6, v4
	v_add_u32_e32 v5, 1, v5
	s_nop 0
	v_cndmask_b32_e32 v3, v3, v7, vcc
	v_sub_u32_e32 v7, v6, v4
	v_cndmask_b32_e32 v6, v6, v7, vcc
	v_add_u32_e32 v7, 1, v3
	v_cmp_ge_u32_e32 vcc, v6, v4
	s_nop 1
	v_cndmask_b32_e32 v3, v3, v7, vcc
	v_mul_lo_u32 v6, v4, v3
	v_add_u32_e32 v4, v6, v4
	v_cmp_ne_u32_e32 vcc, v5, v4
	s_and_saveexec_b64 s[10:11], vcc
	s_xor_b64 s[10:11], exec, s[10:11]
	s_cbranch_execz .LBB0_465
	s_waitcnt lgkmcnt(0)
	v_mad_u32_u24 v6, v3, v2, v2
	s_add_u32 s16, s38, 0x1d6c5400
	s_addc_u32 s17, s39, 0
	v_mov_b32_e32 v2, 0
	s_mov_b32 s44, 0
	global_load_dword v4, v2, s[16:17] sc1
.Lmy_bf_4:
	s_sleep 6
	global_load_dword v5, v2, s[16:17] sc1
	s_waitcnt vmcnt(1)
	v_sub_u32_e32 v4, v4, v6
	v_cmp_gt_i32_e32 vcc, 0, v4
	s_cbranch_vccz .Lmy_bf_4d
	s_sleep 6
	global_load_dword v4, v2, s[16:17] sc1
	s_waitcnt vmcnt(1)
	v_sub_u32_e32 v5, v5, v6
	v_cmp_gt_i32_e32 vcc, 0, v5
	s_cbranch_vccz .Lmy_bf_4d
	s_add_i32 s44, s44, 1
	s_cmp_lt_u32 s44, 0x100000
	s_cbranch_scc1 .Lmy_bf_4

.LBB0_465:
	s_andn2_saveexec_b64 s[10:11], s[10:11]
	s_cbranch_execz .LBB0_483
	buffer_wbl2 sc1
	s_waitcnt lgkmcnt(0)
	v_mad_u32_u24 v6, v3, v2, v2
	s_waitcnt vmcnt(0)
	v_mov_b32_e32 v4, 0x1d6c5000
	v_mov_b32_e32 v5, 1
	global_atomic_add v4, v5, s[38:39] offset:1024
	s_add_u32 s12, s38, 0x1d6c5400
	s_addc_u32 s13, s39, 0
	v_mov_b32_e32 v2, 0
	s_mov_b32 s44, 0
	global_load_dword v4, v2, s[12:13] sc1
.Lmy_bl_4:
	s_sleep 6
	global_load_dword v5, v2, s[12:13] sc1
	s_waitcnt vmcnt(1)
	v_sub_u32_e32 v4, v4, v6
	v_cmp_gt_i32_e32 vcc, 0, v4
	s_cbranch_vccz .Lmy_bl_4d
	s_sleep 6
	global_load_dword v4, v2, s[12:13] sc1
	s_waitcnt vmcnt(1)
	v_sub_u32_e32 v5, v5, v6
	v_cmp_gt_i32_e32 vcc, 0, v5
	s_cbranch_vccz .Lmy_bl_4d
	s_add_i32 s44, s44, 1
	s_cmp_lt_u32 s44, 0x100000
	s_cbranch_scc1 .Lmy_bl_4

.LBB0_1711:
	s_lshl_b32 s6, s3, 8
	s_add_u32 s6, s34, s6
	s_addc_u32 s7, s35, 0
	v_mov_b32_e32 v3, 0x1000
	v_mov_b32_e32 v5, 1
	global_atomic_add v5, v3, v5, s[6:7] offset:1024 sc0
	v_cvt_f32_u32_e32 v3, v4
	v_sub_u32_e32 v6, 0, v4
	v_rcp_iflag_f32_e32 v3, v3
	s_nop 0
	v_mul_f32_e32 v3, 0x4f7ffffe, v3
	v_cvt_u32_f32_e32 v3, v3
	v_mul_lo_u32 v6, v6, v3
	v_mul_hi_u32 v6, v3, v6
	v_add_u32_e32 v3, v3, v6
	s_waitcnt vmcnt(0)
	v_mul_hi_u32 v3, v5, v3
	v_mul_lo_u32 v6, v3, v4
	v_sub_u32_e32 v6, v5, v6
	v_add_u32_e32 v7, 1, v3
	v_cmp_ge_u32_e32 vcc, v6, v4
	v_add_u32_e32 v5, 1, v5
	s_nop 0
	v_cndmask_b32_e32 v3, v3, v7, vcc
	v_sub_u32_e32 v7, v6, v4
	v_cndmask_b32_e32 v6, v6, v7, vcc
	v_add_u32_e32 v7, 1, v3
	v_cmp_ge_u32_e32 vcc, v6, v4
	s_nop 1
	v_cndmask_b32_e32 v3, v3, v7, vcc
	v_mul_lo_u32 v6, v4, v3
	v_add_u32_e32 v4, v6, v4
	v_cmp_ne_u32_e32 vcc, v5, v4
	s_and_saveexec_b64 s[8:9], vcc
	s_xor_b64 s[8:9], exec, s[8:9]
	s_cbranch_execz .LBB0_1725
	s_waitcnt lgkmcnt(0)
	v_mad_u32_u24 v6, v3, v2, v2
	s_add_u32 s14, s38, 0x1d6c5400
	s_addc_u32 s15, s39, 0
	v_mov_b32_e32 v2, 0
	s_mov_b32 s28, 0
	global_load_dword v4, v2, s[14:15] sc1
.Lmy_bf_16:
	s_sleep 6
	global_load_dword v5, v2, s[14:15] sc1
	s_waitcnt vmcnt(1)
	v_sub_u32_e32 v4, v4, v6
	v_cmp_gt_i32_e32 vcc, 0, v4
	s_cbranch_vccz .Lmy_bf_16d
	s_sleep 6
	global_load_dword v4, v2, s[14:15] sc1
	s_waitcnt vmcnt(1)
	v_sub_u32_e32 v5, v5, v6
	v_cmp_gt_i32_e32 vcc, 0, v5
	s_cbranch_vccz .Lmy_bf_16d
	s_add_i32 s28, s28, 1
	s_cmp_lt_u32 s28, 0x100000
	s_cbranch_scc1 .Lmy_bf_16

.LBB0_1725:
	s_andn2_saveexec_b64 s[8:9], s[8:9]
	s_cbranch_execz .LBB0_1743
	buffer_wbl2 sc1
	s_waitcnt lgkmcnt(0)
	v_mad_u32_u24 v6, v3, v2, v2
	s_waitcnt vmcnt(0)
	v_mov_b32_e32 v4, 0x1d6c5000
	v_mov_b32_e32 v5, 1
	global_atomic_add v4, v5, s[38:39] offset:1024
	s_add_u32 s10, s38, 0x1d6c5400
	s_addc_u32 s11, s39, 0
	v_mov_b32_e32 v2, 0
	s_mov_b32 s28, 0
	global_load_dword v4, v2, s[10:11] sc1
.Lmy_bl_16:
	s_sleep 6
	global_load_dword v5, v2, s[10:11] sc1
	s_waitcnt vmcnt(1)
	v_sub_u32_e32 v4, v4, v6
	v_cmp_gt_i32_e32 vcc, 0, v4
	s_cbranch_vccz .Lmy_bl_16d
	s_sleep 6
	global_load_dword v4, v2, s[10:11] sc1
	s_waitcnt vmcnt(1)
	v_sub_u32_e32 v5, v5, v6
	v_cmp_gt_i32_e32 vcc, 0, v5
	s_cbranch_vccz .Lmy_bl_16d
	s_add_i32 s28, s28, 1
	s_cmp_lt_u32 s28, 0x100000
	s_cbranch_scc1 .Lmy_bl_16

.LBB0_2154:
	s_lshl_b32 s3, s3, 8
	s_add_u32 s6, s34, s3
	s_addc_u32 s7, s35, 0
	v_mov_b32_e32 v3, 0x1000
	v_mov_b32_e32 v5, 1
	global_atomic_add v5, v3, v5, s[6:7] offset:1024 sc0
	v_cvt_f32_u32_e32 v3, v4
	v_sub_u32_e32 v6, 0, v4
	v_rcp_iflag_f32_e32 v3, v3
	s_nop 0
	v_mul_f32_e32 v3, 0x4f7ffffe, v3
	v_cvt_u32_f32_e32 v3, v3
	v_mul_lo_u32 v6, v6, v3
	v_mul_hi_u32 v6, v3, v6
	v_add_u32_e32 v3, v3, v6
	s_waitcnt vmcnt(0)
	v_mul_hi_u32 v3, v5, v3
	v_mul_lo_u32 v6, v3, v4
	v_sub_u32_e32 v6, v5, v6
	v_add_u32_e32 v7, 1, v3
	v_cmp_ge_u32_e32 vcc, v6, v4
	v_add_u32_e32 v5, 1, v5
	s_nop 0
	v_cndmask_b32_e32 v3, v3, v7, vcc
	v_sub_u32_e32 v7, v6, v4
	v_cndmask_b32_e32 v6, v6, v7, vcc
	v_add_u32_e32 v7, 1, v3
	v_cmp_ge_u32_e32 vcc, v6, v4
	s_nop 1
	v_cndmask_b32_e32 v3, v3, v7, vcc
	v_mul_lo_u32 v6, v4, v3
	v_add_u32_e32 v4, v6, v4
	v_cmp_ne_u32_e32 vcc, v5, v4
	s_and_saveexec_b64 s[8:9], vcc
	s_xor_b64 s[8:9], exec, s[8:9]
	s_cbranch_execz .LBB0_2168
	s_waitcnt lgkmcnt(0)
	v_mad_u32_u24 v6, v3, v2, v2
	s_add_u32 s14, s38, 0x1d6c5400
	s_addc_u32 s15, s39, 0
	v_mov_b32_e32 v2, 0
	s_mov_b32 s3, 0
	global_load_dword v4, v2, s[14:15] sc1
.Lmy_bf_20:
	s_sleep 6
	global_load_dword v5, v2, s[14:15] sc1
	s_waitcnt vmcnt(1)
	v_sub_u32_e32 v4, v4, v6
	v_cmp_gt_i32_e32 vcc, 0, v4
	s_cbranch_vccz .Lmy_bf_20d
	s_sleep 6
	global_load_dword v4, v2, s[14:15] sc1
	s_waitcnt vmcnt(1)
	v_sub_u32_e32 v5, v5, v6
	v_cmp_gt_i32_e32 vcc, 0, v5
	s_cbranch_vccz .Lmy_bf_20d
	s_add_i32 s3, s3, 1
	s_cmp_lt_u32 s3, 0x100000
	s_cbranch_scc1 .Lmy_bf_20

.LBB0_2168:
	s_andn2_saveexec_b64 s[8:9], s[8:9]
	s_cbranch_execz .LBB0_2186
	buffer_wbl2 sc1
	s_waitcnt lgkmcnt(0)
	v_mad_u32_u24 v6, v3, v2, v2
	s_waitcnt vmcnt(0)
	v_mov_b32_e32 v4, 0x1d6c5000
	v_mov_b32_e32 v5, 1
	global_atomic_add v4, v5, s[38:39] offset:1024
	s_add_u32 s10, s38, 0x1d6c5400
	s_addc_u32 s11, s39, 0
	v_mov_b32_e32 v2, 0
	s_mov_b32 s3, 0
	global_load_dword v4, v2, s[10:11] sc1
.Lmy_bl_20:
	s_sleep 6
	global_load_dword v5, v2, s[10:11] sc1
	s_waitcnt vmcnt(1)
	v_sub_u32_e32 v4, v4, v6
	v_cmp_gt_i32_e32 vcc, 0, v4
	s_cbranch_vccz .Lmy_bl_20d
	s_sleep 6
	global_load_dword v4, v2, s[10:11] sc1
	s_waitcnt vmcnt(1)
	v_sub_u32_e32 v5, v5, v6
	v_cmp_gt_i32_e32 vcc, 0, v5
	s_cbranch_vccz .Lmy_bl_20d
	s_add_i32 s3, s3, 1
	s_cmp_lt_u32 s3, 0x100000
	s_cbranch_scc1 .Lmy_bl_20
